# H (up-GEMM output, down-GEMM A operand) stored K-tile-blocked [row panel][k-tile][256 rows][64 cols]: P4 epilogue stores and P5 A-operand LDS-DMA reads become contiguous; same math, same bf16 storage
# speedup vs baseline: 1.0005x; 1.0005x over previous
;     __device__ __forceinline__ void operator()(const f32x4 (&acc)[2][2][4][2], const Unit& u, int wr, int wc, int fr, int fq) const {
;         const int row0 = u.pm * BM + wr * 64 + fr; const int col0 = u.pn * BM + wc * 32 + 8 * fq;
; template <class Epi, class Sched, bool ALIGN_EPI = false, bool SP2 = false>
; __device__ __forceinline__ void gemm_phase(PG8_LAS unsigned char* lds, const Gemm g, const Sched& S, const Epi& E) {
;     const int tid = threadIdx.x, wid = __builtin_amdgcn_readfirstlane(tid >> 6), lane = tid & 63, wr = wid >> 2, wc = wid & 3, fr = lane & 15, fq = lane >> 4;
;     const int K = g.K, nt = K / BK;
;     unsigned voffA[2], voffB[2];
; #pragma unroll
;     for (int i = 0; i < 2; ++i) { int R, C; stage_rc(tid * 16 + i * 8192, R, C); const int Rb = Epi::PERM ? ((R & ~31) + perm32(R & 31)) : R;
;         voffA[i] = (unsigned)(R * K + C) * 2u; voffB[i] = (unsigned)(Rb * K + C) * 2u; }
;     const size_t kstep = (size_t)(BK * 2);
;     const size_t hstep = (size_t)HALF * K * 2;
;     const size_t tstep = 2 * hstep;
;     const unsigned ldsw = (unsigned)wid * 1024u;
;     const int aoff = lds_byte(wr * 64 + fr, fq * 8), boff = lds_byte(wc * 32 + fr, fq * 8);
.LBB0_1373:
	s_lshl_b32 s0, s10, 5
	s_mov_b64 s[10:11], 0x80
	s_and_b32 s17, s0, 0x60
	s_and_b32 s70, s17, 32
	s_and_b32 s71, s17, 64
	s_lshl_b32 s71, s71, 8
	s_or_b32 s70, s70, s71
	s_mov_b64 s[58:59], 0x10000
	s_add_i32 m0, s34, 0x18000
	v_lshl_add_u64 v[8:9], v[8:9], 0, s[10:11]
	s_lshl_b32 s13, s14, 13
	s_lshl_b32 s18, s17, 7
	s_waitcnt vmcnt(2)
	s_barrier
	global_load_lds_dwordx4 v[8:9], off
	v_lshl_add_u64 v[4:5], v[4:5], 0, s[10:11]
	s_add_i32 m0, s34, 0x1a000
	s_add_i32 s38, s34, 0x8000
	s_add_i32 s39, s34, 0xa000
	global_load_lds_dwordx4 v[4:5], off
	v_lshl_add_u64 v[2:3], v[2:3], 0, s[10:11]
	s_mov_b32 m0, s38
	s_add_u32 s0, s26, 0x40080
	global_load_lds_dwordx4 v[2:3], off
	v_lshl_add_u64 v[2:3], v[6:7], 0, s[10:11]
	s_mov_b32 m0, s39
	s_addc_u32 s1, s27, 0
	global_load_lds_dwordx4 v[2:3], off
	s_add_i32 m0, s34, 0x1c000
	v_lshl_add_u64 v[2:3], s[0:1], 0, v[132:133]
	global_load_lds_dwordx4 v[2:3], off
	v_lshl_add_u64 v[2:3], s[0:1], 0, v[136:137]
	s_add_i32 m0, s34, 0x1e000
	v_bfe_u32 v4, v208, 4, 2
	global_load_lds_dwordx4 v[2:3], off
	v_and_b32_e32 v3, 15, v208
	v_lshlrev_b32_e32 v2, 4, v4
	v_lshlrev_b32_e32 v6, 2, v3
	v_lshl_or_b32 v1, s14, 6, v3
	v_lshl_or_b32 v5, v3, 6, v2
	v_and_b32_e32 v3, 32, v6
	v_bitop3_b32 v5, v5, s13, v3 bitop3:0xde
	v_lshlrev_b32_e32 v3, 6, v208
	s_movk_i32 s0, 0x3c0
	v_lshlrev_b32_e32 v7, 2, v208
	v_and_or_b32 v3, v3, s0, v2
	v_and_b32_e32 v7, 32, v7
	v_bitop3_b32 v7, s18, v3, v7 bitop3:0xf6
	v_mov_b32_e32 v3, v133
	v_lshl_add_u64 v[138:139], s[8:9], 0, v[2:3]
	v_lshlrev_b32_e32 v2, 8, v208
	v_and_b32_e32 v2, 0x38000, v2
	v_lshlrev_b32_e32 v3, 11, v12
	v_or3_b32 v2, v10, v2, v3
	s_cmpk_lt_u32 s12, 0x100
	v_add_u32_e32 v140, v2, v11
	v_lshlrev_b32_e32 v2, 4, v13
	s_cselect_b64 s[12:13], -1, 0
	s_lshl_b32 s8, s14, 8
	v_and_b32_e32 v2, 0x78000, v2
	s_mov_b32 s0, 0x18000
	s_mov_b32 s1, 0x1c000
	s_waitcnt vmcnt(6)
	s_addk_i32 s8, 0x100
	v_or3_b32 v2, v10, v2, v3
	s_add_i32 s8, s8, 0x20800
	v_add_u32_e32 v142, v2, v11
	s_add_i32 s41, s15, 0x100
	s_add_i32 s44, s16, 0x100
	s_add_i32 s45, s0, 0x100
	s_add_i32 s46, s1, 0x100
	v_mbcnt_lo_u32_b32 v2, -1, 0
	v_add_u32_e32 v151, s8, v6
	v_lshl_or_b32 v152, v4, 3, s70
	v_mov_b32_e32 v141, v133
	v_mov_b32_e32 v143, v133
	s_mov_b32 s23, 0
	s_movk_i32 s40, 0x181
	v_add_u32_e32 v153, s41, v7
	v_add_u32_e32 v154, s44, v7
	v_add_u32_e32 v155, 0x100, v5
	v_mov_b32_e32 v156, 0x358637bd
	v_mov_b64_e32 v[144:145], 0xbff
	v_add_u32_e32 v157, s45, v7
	v_add_u32_e32 v158, s46, v7
	v_mbcnt_hi_u32_b32 v159, -1, v2
	s_mov_b32 s47, 0
	s_barrier
	s_branch .LBB0_1376
